# EpiInEven/EpiInOdd: 8 serialized SS loads issued together (one wait) + coalesced sample_gemm
# speedup vs baseline: 1.0732x; 1.0027x over previous
; DI float row_rstd(const float* SS, int row) { return rsqrtf(SS[row] * (1.0f / 1024.0f) + 1e-6f); }
;     DI void operator()(const Acc& acc, const pg8::Unit& u, int wr, int wc, int fr, int fq) const {
;         const int row0 = u.pm * 256 + wr * 64 + fr, cl = wc * 32 + fq * 8;
;         float rsv[2][4];
; #pragma unroll
;         for (int ai = 0; ai < 2; ++ai)
; #pragma unroll
;             for (int m = 0; m < 4; ++m) rsv[ai][m] = row_rstd(SS, row0 + ai * 128 + m * 16);
;         if (u.pn < 8) {
.LBB0_296:
	v_lshl_add_u32 v154, s78, 8, v188
	v_ashrrev_i32_e32 v155, 31, v154
	v_lshl_add_u64 v[148:149], v[154:155], 2, s[6:7]
	global_load_dword v234, v[148:149], off
	v_or_b32_e32 v158, 16, v154
	v_ashrrev_i32_e32 v159, 31, v158
	v_or_b32_e32 v162, 32, v154
	v_ashrrev_i32_e32 v163, 31, v162
	v_or_b32_e32 v166, 48, v154
	v_ashrrev_i32_e32 v167, 31, v166
	v_add_u32_e32 v182, 0x80, v154
	v_add_u32_e32 v196, 0x90, v154
	v_add_u32_e32 v198, 0xa0, v154
	v_add_u32_e32 v180, 0xb0, v154
	v_ashrrev_i32_e32 v183, 31, v182
	v_ashrrev_i32_e32 v197, 31, v196
	v_ashrrev_i32_e32 v199, 31, v198
	v_ashrrev_i32_e32 v181, 31, v180
	s_mov_b64 s[78:79], -1
	s_cmp_gt_i32 s4, 7
	v_lshlrev_b64 v[178:179], 10, v[154:155]
	v_lshlrev_b64 v[176:177], 10, v[158:159]
	v_lshlrev_b64 v[174:175], 10, v[162:163]
	v_lshlrev_b64 v[172:173], 10, v[166:167]
	v_lshlrev_b64 v[154:155], 10, v[198:199]
	v_lshl_add_u64 v[150:151], v[158:159], 2, s[6:7]
	global_load_dword v235, v[150:151], off
	v_lshl_add_u64 v[150:151], v[162:163], 2, s[6:7]
	global_load_dword v236, v[150:151], off
	v_lshl_add_u64 v[150:151], v[166:167], 2, s[6:7]
	global_load_dword v237, v[150:151], off
	global_load_dword v238, v[148:149], off offset:512
	global_load_dword v239, v[148:149], off offset:576
	global_load_dword v240, v[148:149], off offset:640
	global_load_dword v241, v[148:149], off offset:704
	s_waitcnt vmcnt(0)
	v_fmamk_f32 v138, v234, 0x3a800000, v195
	v_cmp_gt_f32_e32 vcc, s97, v138
	v_mul_f32_e32 v150, 0x4b800000, v138
	s_nop 0
	v_cndmask_b32_e32 v138, v138, v150, vcc
	v_rsq_f32_e32 v138, v138
	s_nop 0
	v_mul_f32_e32 v150, 0x45800000, v138
	v_cndmask_b32_e32 v170, v138, v150, vcc
	v_lshlrev_b64 v[158:159], 10, v[180:181]
	v_fmamk_f32 v138, v235, 0x3a800000, v195
	v_cmp_gt_f32_e32 vcc, s97, v138
	v_mul_f32_e32 v150, 0x4b800000, v138
	s_nop 0
	v_cndmask_b32_e32 v138, v138, v150, vcc
	v_rsq_f32_e32 v138, v138
	s_nop 0
	v_mul_f32_e32 v150, 0x45800000, v138
	v_cndmask_b32_e32 v168, v138, v150, vcc
	v_lshlrev_b64 v[162:163], 10, v[196:197]
	v_fmamk_f32 v138, v236, 0x3a800000, v195
	v_cmp_gt_f32_e32 vcc, s97, v138
	v_mul_f32_e32 v150, 0x4b800000, v138
	s_nop 0
	v_cndmask_b32_e32 v138, v138, v150, vcc
	v_rsq_f32_e32 v138, v138
	s_nop 0
	v_mul_f32_e32 v150, 0x45800000, v138
	v_cndmask_b32_e32 v164, v138, v150, vcc
	v_lshlrev_b64 v[166:167], 10, v[182:183]
	v_fmamk_f32 v138, v237, 0x3a800000, v195
	v_cmp_gt_f32_e32 vcc, s97, v138
	v_mul_f32_e32 v150, 0x4b800000, v138
	s_nop 0
	v_cndmask_b32_e32 v138, v138, v150, vcc
	v_rsq_f32_e32 v138, v138
	s_nop 0
	v_mul_f32_e32 v150, 0x45800000, v138
	v_cndmask_b32_e32 v160, v138, v150, vcc
	v_fmamk_f32 v138, v238, 0x3a800000, v195
	v_cmp_gt_f32_e32 vcc, s97, v138
	v_mul_f32_e32 v150, 0x4b800000, v138
	s_nop 0
	v_cndmask_b32_e32 v138, v138, v150, vcc
	v_rsq_f32_e32 v138, v138
	s_nop 0
	v_mul_f32_e32 v150, 0x45800000, v138
	v_cndmask_b32_e32 v156, v138, v150, vcc
	v_fmamk_f32 v138, v239, 0x3a800000, v195
	v_cmp_gt_f32_e32 vcc, s97, v138
	v_mul_f32_e32 v150, 0x4b800000, v138
	s_nop 0
	v_cndmask_b32_e32 v138, v138, v150, vcc
	v_rsq_f32_e32 v138, v138
	s_nop 0
	v_mul_f32_e32 v150, 0x45800000, v138
	v_cndmask_b32_e32 v152, v138, v150, vcc
	v_fmamk_f32 v138, v240, 0x3a800000, v195
	v_cmp_gt_f32_e32 vcc, s97, v138
	v_mul_f32_e32 v150, 0x4b800000, v138
	s_nop 0
	v_cndmask_b32_e32 v138, v138, v150, vcc
	v_rsq_f32_e32 v138, v138
	s_nop 0
	v_mul_f32_e32 v150, 0x45800000, v138
	v_cndmask_b32_e32 v150, v138, v150, vcc
	v_fmamk_f32 v138, v241, 0x3a800000, v195
	v_cmp_gt_f32_e32 vcc, s97, v138
	v_mul_f32_e32 v148, 0x4b800000, v138
	s_nop 0
	v_cndmask_b32_e32 v138, v138, v148, vcc
	v_rsq_f32_e32 v138, v138
	s_nop 0
	v_mul_f32_e32 v148, 0x45800000, v138
	v_cndmask_b32_e32 v148, v138, v148, vcc
	s_cbranch_scc1 .LBB0_299
	s_andn2_b64 vcc, exec, s[78:79]
	s_cbranch_vccz .LBB0_300

; DI u32x4 pk8(f32x4 a, f32x4 b) { u32x4 w; w.x = pk2(a[0], a[1]); w.y = pk2(a[2], a[3]); w.z = pk2(b[0], b[1]); w.w = pk2(b[2], b[3]); return w; }
; DI float row_rstd(const float* SS, int row) { return rsqrtf(SS[row] * (1.0f / 1024.0f) + 1e-6f); }
;     DI void operator()(const Acc& acc, const pg8::Unit& u, int wr, int wc, int fr, int fq) const {
;         const int typ = u.pn >> 1, ph = u.pn & 1;
;         bf16_t* O = QKVUS + (size_t)typ * ((size_t)MT * MW);
;         const bool samp = (u.pm == 128);
;         const bool keep = samp || ((u.pm & 15) >= 14);
;         float rsv[2][4];
; #pragma unroll
;         for (int ai = 0; ai < 2; ++ai)
; #pragma unroll
;             for (int m = 0; m < 4; ++m) rsv[ai][m] = row_rstd(SS, u.pm * 256 + ai * 128 + wr * 64 + m * 16 + fr);
;     ...
; #pragma unroll
;             for (int ai = 0; ai < 2; ++ai)
; #pragma unroll
;                 for (int m = 0; m < 4; ++m) {
;                     const int row = u.pm * 256 + ai * 128 + wr * 64 + m * 16 + fr;
;                     const float rs = rsv[ai][m];
;                     float s1 = 0.f, s2 = 0.f;
; #pragma unroll
;                     for (int bj = 0; bj < 2; ++bj) {
;                         const f32x4 o0 = acc[ai][bj][m][0] * rs, o1 = acc[ai][bj][m][1] * rs;
;                         const int col = ph * 256 + bj * 128 + wc * 32 + fq * 8;
;                         *(u32x4*)(O + (size_t)row * MW + col) = pk8(o0, o1);
;                         if (typ == 4) {
;                             s1 += (o0[0] + o0[1]) + (o0[2] + o0[3]) + (o1[0] + o1[1]) + (o1[2] + o1[3]);
;                             s2 += (o0[0] * o0[0] + o0[1] * o0[1]) + (o0[2] * o0[2] + o0[3] * o0[3]) + (o1[0] * o1[0] + o1[1] * o1[1]) + (o1[2] * o1[2] + o1[3] * o1[3]);
;                         }
.LBB0_790:
	s_ashr_i32 s55, s86, 1
	s_mul_i32 s5, s55, 0x2040000
	s_mul_hi_i32 s4, s55, 0x2040000
	s_add_u32 s88, s24, s5
	s_addc_u32 s89, s25, s4
	s_and_b32 s4, s84, 14
	s_cmp_eq_u32 s4, 14
	s_cselect_b64 s[6:7], -1, 0
	s_lshl_b32 s73, s84, 8
	v_add_u32_e32 v180, s73, v216
	v_ashrrev_i32_e32 v181, 31, v180
	v_lshl_add_u64 v[130:131], v[180:181], 2, s[16:17]
	global_load_dword v240, v[130:131], off
	v_or_b32_e32 v192, 16, v180
	v_ashrrev_i32_e32 v193, 31, v192
	v_or_b32_e32 v188, 32, v180
	v_ashrrev_i32_e32 v189, 31, v188
	v_or_b32_e32 v184, 48, v180
	v_ashrrev_i32_e32 v185, 31, v184
	v_add_u32_e32 v178, 0x80, v180
	v_ashrrev_i32_e32 v179, 31, v178
	v_add_u32_e32 v174, 0x90, v180
	v_ashrrev_i32_e32 v175, 31, v174
	v_add_u32_e32 v170, 0xa0, v180
	v_ashrrev_i32_e32 v171, 31, v170
	v_add_u32_e32 v166, 0xb0, v180
	v_ashrrev_i32_e32 v167, 31, v166
	s_and_b32 s79, s86, 1
	s_cmpk_eq_i32 s84, 0x80
	s_cselect_b64 s[4:5], -1, 0
	s_or_b64 s[90:91], s[4:5], s[6:7]
	s_mov_b64 s[6:7], -1
	s_cmp_lt_i32 s55, 2
	v_lshlrev_b64 v[198:199], 10, v[180:181]
	v_lshl_add_u64 v[130:131], v[192:193], 2, s[16:17]
	global_load_dword v241, v[130:131], off
	v_lshl_add_u64 v[130:131], v[188:189], 2, s[16:17]
	global_load_dword v242, v[130:131], off
	v_lshl_add_u64 v[130:131], v[184:185], 2, s[16:17]
	global_load_dword v243, v[130:131], off
	v_lshl_add_u64 v[130:131], v[178:179], 2, s[16:17]
	global_load_dword v244, v[130:131], off
	v_lshl_add_u64 v[130:131], v[174:175], 2, s[16:17]
	global_load_dword v245, v[130:131], off
	v_lshl_add_u64 v[130:131], v[170:171], 2, s[16:17]
	global_load_dword v246, v[130:131], off
	v_lshl_add_u64 v[130:131], v[166:167], 2, s[16:17]
	global_load_dword v248, v[130:131], off
	s_waitcnt vmcnt(0)
	v_fmamk_f32 v130, v240, 0x3a800000, v223
	v_cmp_gt_f32_e32 vcc, s71, v130
	v_mul_f32_e32 v131, 0x4b800000, v130
	s_nop 0
	v_cndmask_b32_e32 v130, v130, v131, vcc
	v_rsq_f32_e32 v130, v130
	s_nop 0
	v_mul_f32_e32 v131, 0x45800000, v130
	v_cndmask_b32_e32 v196, v130, v131, vcc
	v_fmamk_f32 v130, v241, 0x3a800000, v223
	v_cmp_gt_f32_e32 vcc, s71, v130
	v_mul_f32_e32 v131, 0x4b800000, v130
	s_nop 0
	v_cndmask_b32_e32 v130, v130, v131, vcc
	v_rsq_f32_e32 v130, v130
	s_nop 0
	v_mul_f32_e32 v131, 0x45800000, v130
	v_cndmask_b32_e32 v194, v130, v131, vcc
	v_fmamk_f32 v130, v242, 0x3a800000, v223
	v_cmp_gt_f32_e32 vcc, s71, v130
	v_mul_f32_e32 v131, 0x4b800000, v130
	s_nop 0
	v_cndmask_b32_e32 v130, v130, v131, vcc
	v_rsq_f32_e32 v130, v130
	s_nop 0
	v_mul_f32_e32 v131, 0x45800000, v130
	v_cndmask_b32_e32 v190, v130, v131, vcc
	v_fmamk_f32 v130, v243, 0x3a800000, v223
	v_cmp_gt_f32_e32 vcc, s71, v130
	v_mul_f32_e32 v131, 0x4b800000, v130
	s_nop 0
	v_cndmask_b32_e32 v130, v130, v131, vcc
	v_rsq_f32_e32 v130, v130
	s_nop 0
	v_mul_f32_e32 v131, 0x45800000, v130
	v_cndmask_b32_e32 v186, v130, v131, vcc
	v_fmamk_f32 v130, v244, 0x3a800000, v223
	v_cmp_gt_f32_e32 vcc, s71, v130
	v_mul_f32_e32 v131, 0x4b800000, v130
	s_nop 0
	v_cndmask_b32_e32 v130, v130, v131, vcc
	v_rsq_f32_e32 v130, v130
	s_nop 0
	v_mul_f32_e32 v131, 0x45800000, v130
	v_cndmask_b32_e32 v182, v130, v131, vcc
	v_fmamk_f32 v130, v245, 0x3a800000, v223
	v_cmp_gt_f32_e32 vcc, s71, v130
	v_mul_f32_e32 v131, 0x4b800000, v130
	s_nop 0
	v_cndmask_b32_e32 v130, v130, v131, vcc
	v_rsq_f32_e32 v130, v130
	s_nop 0
	v_mul_f32_e32 v131, 0x45800000, v130
	v_cndmask_b32_e32 v176, v130, v131, vcc
	v_fmamk_f32 v130, v246, 0x3a800000, v223
	v_cmp_gt_f32_e32 vcc, s71, v130
	v_mul_f32_e32 v131, 0x4b800000, v130
	s_nop 0
	v_cndmask_b32_e32 v130, v130, v131, vcc
	v_rsq_f32_e32 v130, v130
	s_nop 0
	v_mul_f32_e32 v131, 0x45800000, v130
	v_cndmask_b32_e32 v172, v130, v131, vcc
	v_fmamk_f32 v130, v248, 0x3a800000, v223
	v_cmp_gt_f32_e32 vcc, s71, v130
	v_mul_f32_e32 v131, 0x4b800000, v130
	s_nop 0
	v_cndmask_b32_e32 v130, v130, v131, vcc
	v_rsq_f32_e32 v130, v130
	s_nop 0
	v_mul_f32_e32 v131, 0x45800000, v130
	v_cndmask_b32_e32 v168, v130, v131, vcc
	s_cbranch_scc1 .LBB0_895
	v_lshl_or_b32 v138, s79, 8, v219
	s_cmp_eq_u32 s55, 4
	s_cselect_b64 s[96:97], -1, 0
	v_lshl_add_u64 v[144:145], s[88:89], 0, v[198:199]
	v_pk_mul_f32 v[132:133], v[128:129], v[196:197] op_sel_hi:[1,0]
	v_pk_mul_f32 v[130:131], v[126:127], v[196:197] op_sel_hi:[1,0]
	v_pk_mul_f32 v[136:137], v[124:125], v[196:197] op_sel_hi:[1,0]
	v_pk_mul_f32 v[134:135], v[122:123], v[196:197] op_sel_hi:[1,0]
	v_lshlrev_b32_e32 v154, 1, v138
	v_cvt_pk_bf16_f32 v140, v130, v131
	v_cvt_pk_bf16_f32 v141, v132, v133
	v_cvt_pk_bf16_f32 v142, v134, v135
	v_cvt_pk_bf16_f32 v143, v136, v137
	v_lshl_add_u64 v[202:203], v[144:145], 0, v[154:155]
	s_and_b64 vcc, exec, s[96:97]
	global_store_dwordx4 v[202:203], v[140:143], off
	s_cbranch_vccz .LBB0_793
	s_nop 0
	v_mov_b32_e32 v140, v131
	v_mov_b32_e32 v141, v132
	v_mov_b32_e32 v142, v130
	v_mov_b32_e32 v143, v133
	v_pk_add_f32 v[140:141], v[140:141], v[142:143]
	v_mul_f32_e32 v142, v130, v130
	v_pk_fma_f32 v[142:143], v[130:131], v[130:131], v[142:143] op_sel_hi:[1,1,0]
	v_mul_f32_e32 v139, v134, v134
	v_mul_f32_e32 v142, v132, v132
	v_pk_fma_f32 v[144:145], v[132:133], v[132:133], v[142:143] op_sel_hi:[1,1,0]
	v_mov_b32_e32 v142, v136
	v_mov_b32_e32 v144, v137
	v_pk_add_f32 v[142:143], v[142:143], v[144:145]
	v_pk_add_f32 v[144:145], v[134:135], v[134:135] op_sel:[1,0]
	v_pk_mul_f32 v[200:201], v[134:135], v[134:135]
	v_pk_add_f32 v[140:141], v[140:141], v[140:141] op_sel:[0,1] op_sel_hi:[1,0]
	v_mov_b32_e32 v145, v201
	v_mov_b32_e32 v141, v139
	v_pk_add_f32 v[140:141], v[144:145], v[140:141]
	s_nop 0
	v_pk_add_f32 v[140:141], v[140:141], v[142:143]
	v_mul_f32_e32 v142, v136, v136
	v_pk_fma_f32 v[142:143], v[136:137], v[136:137], v[142:143] op_sel_hi:[1,1,0]
	s_nop 0
	v_mov_b32_e32 v142, v155
	v_pk_add_f32 v[142:143], v[140:141], v[142:143]
	s_branch .LBB0_794
